# k_rope/row-stat loop: all eight loads of a row issued together with counted vmcnt (was five serialized load-wait round trips per row)
# baseline (speedup 1.0000x reference)
; #define GAS __attribute__((address_space(1)))
; __device__ __forceinline__ unsigned cvt_pk_bf16(float lo, float hi) { unsigned r; asm volatile("v_cvt_pk_bf16_f32 %0, %1, %2" : "=v"(r) : "v"(lo), "v"(hi)); return r; }
; __device__ __forceinline__ float bflo(unsigned w) { return __uint_as_float(w << 16); }
; __device__ __forceinline__ float bfhi(unsigned w) { return __uint_as_float(w & 0xffff0000u); }
; __global__ void __launch_bounds__(512, 2) fwd_kernel(Args args) {
;     ...
;                 for (int m = gw; m < CH; m += NGW) {
;                     const GAS unsigned* zr = (const GAS unsigned*)(Zb + (size_t)m * ZLD);
;                     float sq = 0.f, skv = 0.f;
; #pragma unroll
;                     for (int j = 0; j < 3; ++j) { const unsigned w = zr[lane + 64 * j]; const float a = bflo(w), b = bfhi(w); sq += a * a + b * b; }
; #pragma unroll
;                     for (int j = 0; j < 2; ++j) { const unsigned w = zr[192 + lane + 64 * j]; const float a = bflo(w), b = bfhi(w); skv += a * a + b * b; }
;                     sq = wave_sum(sq); skv = wave_sum(skv);
;                     if (lane == 0) { RSTD[2 * m] = 1.0f / sqrtf(sq * (1.f / 384.f) + EPS); RSTD[2 * m + 1] = 1.0f / sqrtf(skv * (1.f / 256.f) + EPS); }
;                     const int seq = m >> P.Sshift, pos = m & (P.S - 1);
;                     unsigned pr = 0u;
;                     { const int i = lane & 15; const unsigned w = zr[320 + i]; const float a = bflo(w), b = bfhi(w); const float cs = ROPE[pos * 16 + i], sn = ROPE[131072 + pos * 16 + i];
;                       pr = cvt_pk_bf16(a * cs - b * sn, a * sn + b * cs); }
;                     u32x4 o; const int b4 = 4 * (lane & 3);
;                     o.x = __shfl(pr, b4); o.y = __shfl(pr, b4 + 1); o.z = __shfl(pr, b4 + 2); o.w = __shfl(pr, b4 + 3);
;                     const int head = lane >> 2;
;                     *(GAS u32x4*)(KFb + ((size_t)((seq * 16 + head) << P.Sshift) + pos) * 96 + 64 + 8 * (lane & 3)) = o;
;                 }
.LBB0_88:
	s_or_b64 exec, exec, s[24:25]
	s_ashr_i32 s0, s13, s82
	v_lshl_or_b32 v14, s0, 4, v9
	v_lshlrev_b32_e32 v14, s82, v14
	v_ashrrev_i32_e32 v15, 31, v14
	v_lshl_add_u64 v[14:15], v[14:15], 0, s[4:5]
	v_mad_u64_u32 v[16:17], s[0:1], v14, s75, v[2:3]
	v_mad_i32_i24 v17, v15, s75, v17
	s_add_i32 s13, s13, s49
	s_mul_i32 s0, s49, 0x2800
	s_add_u32 s16, s16, s0
	s_mul_hi_i32 s0, s49, 0x2800
	s_addc_u32 s17, s17, s0
	s_add_i32 s18, s18, s2
	s_cmpk_gt_i32 s13, 0x3fff
	s_waitcnt vmcnt(0)
	v_lshlrev_b32_e32 v14, 16, v22
	v_and_b32_e32 v15, 0xffff0000, v22
	v_mul_f32_e32 v20, v23, v14
	v_mul_f32_e32 v21, v28, v15
	v_mul_f32_e32 v12, v28, v14
	v_mul_f32_e32 v13, v23, v15
	v_sub_f32_e32 v11, v20, v21
	v_add_f32_e32 v12, v12, v13
	v_cvt_pk_bf16_f32 v11, v11, v12
	ds_bpermute_b32 v12, v5, v11
	ds_bpermute_b32 v13, v6, v11
	ds_bpermute_b32 v14, v7, v11
	ds_bpermute_b32 v15, v8, v11
	s_waitcnt lgkmcnt(0)
	global_store_dwordx4 v[16:17], v[12:15], off offset:128
	s_cbranch_scc1 .LBB0_100
.LBB0_89:
	s_and_b32 s4, s13, s3
	s_lshl_b32 s0, s4, 4
	v_or_b32_e32 v168, s0, v0
	v_lshlrev_b32_e32 v22, 2, v0
	v_lshl_add_u64 v[24:25], v[168:169], 2, s[42:43]
	v_add_u32_e32 v168, s0, v4
	v_lshl_add_u64 v[26:27], v[168:169], 2, s[42:43]
	global_load_dword v11, v10, s[16:17]
	global_load_dword v13, v10, s[16:17] offset:256
	global_load_dword v18, v10, s[16:17] offset:512
	global_load_dword v19, v10, s[16:17] offset:768
	global_load_dword v20, v10, s[16:17] offset:1024
	global_load_dword v22, v22, s[16:17] offset:1280
	global_load_dword v23, v[24:25], off
	global_load_dword v28, v[26:27], off
	s_waitcnt vmcnt(6)
	v_lshlrev_b32_e32 v12, 16, v11
	v_lshlrev_b32_e32 v14, 16, v13
	v_and_b32_e32 v13, 0xffff0000, v13
	v_mul_f32_e32 v13, v13, v13
	v_fmac_f32_e32 v13, v14, v14
	v_and_b32_e32 v11, 0xffff0000, v11
	v_mul_f32_e32 v11, v11, v11
	v_fmac_f32_e32 v11, v12, v12
	v_add_f32_e32 v11, v11, v13
	s_waitcnt vmcnt(5)
	v_lshlrev_b32_e32 v15, 16, v18
	v_and_b32_e32 v14, 0xffff0000, v18
	v_mul_f32_e32 v14, v14, v14
	v_fmac_f32_e32 v14, v15, v15
	v_add_f32_e32 v11, v11, v14
	s_waitcnt vmcnt(4)
	v_lshlrev_b32_e32 v16, 16, v19
	v_and_b32_e32 v15, 0xffff0000, v19
	v_mul_f32_e32 v15, v15, v15
	v_fmac_f32_e32 v15, v16, v16
	s_waitcnt vmcnt(3)
	v_lshlrev_b32_e32 v17, 16, v20
	v_and_b32_e32 v16, 0xffff0000, v20
	v_add_f32_dpp v11, v11, v11 row_ror:1 row_mask:0xf bank_mask:0xf bound_ctrl:1
	v_mul_f32_e32 v16, v16, v16
	v_fmac_f32_e32 v16, v17, v17
	v_add_f32_e32 v15, v15, v16
	v_add_f32_dpp v11, v11, v11 row_ror:2 row_mask:0xf bank_mask:0xf bound_ctrl:1
	s_nop 0
	v_add_f32_dpp v13, v15, v15 row_ror:1 row_mask:0xf bank_mask:0xf bound_ctrl:1
	v_add_f32_dpp v11, v11, v11 row_ror:4 row_mask:0xf bank_mask:0xf bound_ctrl:1
	s_nop 0
	v_add_f32_dpp v13, v13, v13 row_ror:2 row_mask:0xf bank_mask:0xf bound_ctrl:1
	v_add_f32_dpp v11, v11, v11 row_ror:8 row_mask:0xf bank_mask:0xf bound_ctrl:1
	ds_bpermute_b32 v12, v1, v11
	v_add_f32_dpp v13, v13, v13 row_ror:4 row_mask:0xf bank_mask:0xf bound_ctrl:1
	s_waitcnt lgkmcnt(0)
	v_add_f32_e32 v11, v11, v12
	v_add_f32_dpp v13, v13, v13 row_ror:8 row_mask:0xf bank_mask:0xf bound_ctrl:1
	ds_bpermute_b32 v14, v1, v13
	v_mov_b32_e32 v12, v11
	s_nop 1
	v_permlane32_swap_b32_e32 v11, v12
	s_waitcnt lgkmcnt(0)
	v_add_f32_e32 v13, v13, v14
	v_mov_b32_e32 v14, v13
	s_nop 1
	v_permlane32_swap_b32_e32 v13, v14
	s_and_saveexec_b64 s[24:25], s[36:37]
	s_cbranch_execz .LBB0_88
	v_add_f32_e32 v11, v11, v12
	v_fmamk_f32 v11, v11, 0x3b2aaaab, v175
	v_cmp_gt_f32_e32 vcc, s76, v11
	v_mul_f32_e32 v12, 0x4f800000, v11
	v_add_f32_e32 v13, v13, v14
	v_cndmask_b32_e32 v11, v11, v12, vcc
	v_sqrt_f32_e32 v12, v11
	s_ashr_i32 s19, s18, 31
	v_add_u32_e32 v14, -1, v12
	v_fma_f32 v15, -v14, v12, v11
	v_cmp_ge_f32_e64 s[0:1], 0, v15
	v_add_u32_e32 v15, 1, v12
	s_nop 0
	v_cndmask_b32_e64 v14, v12, v14, s[0:1]
	v_fma_f32 v12, -v15, v12, v11
	v_cmp_lt_f32_e64 s[0:1], 0, v12
	s_nop 1
	v_cndmask_b32_e64 v12, v14, v15, s[0:1]
	v_mul_f32_e32 v14, 0x37800000, v12
	v_cndmask_b32_e32 v12, v12, v14, vcc
	v_cmp_class_f32_e32 vcc, v11, v185
	s_lshl_b64 s[0:1], s[18:19], 2
	s_add_u32 s34, s92, s0
	v_cndmask_b32_e32 v11, v12, v11, vcc
	v_fmamk_f32 v12, v13, 0x3b800000, v175
	v_cmp_gt_f32_e32 vcc, s76, v12
	v_mul_f32_e32 v13, 0x4f800000, v12
	s_addc_u32 s35, s93, s1
	v_cndmask_b32_e32 v12, v12, v13, vcc
	v_sqrt_f32_e32 v13, v12
	s_nop 0
	v_add_u32_e32 v14, -1, v13
	v_fma_f32 v15, -v14, v13, v12
	v_cmp_ge_f32_e64 s[0:1], 0, v15
	v_add_u32_e32 v15, 1, v13
	s_nop 0
	v_cndmask_b32_e64 v14, v13, v14, s[0:1]
	v_fma_f32 v13, -v15, v13, v12
	v_cmp_lt_f32_e64 s[0:1], 0, v13
	s_nop 1
	v_cndmask_b32_e64 v13, v14, v15, s[0:1]
	v_mul_f32_e32 v14, 0x37800000, v13
	v_cndmask_b32_e32 v13, v13, v14, vcc
	v_cmp_class_f32_e32 vcc, v12, v185
	s_nop 1
	v_cndmask_b32_e32 v12, v13, v12, vcc
	v_div_scale_f32 v13, s[0:1], v12, v12, 1.0
	v_rcp_f32_e32 v14, v13
	s_nop 0
	v_fma_f32 v15, -v13, v14, 1.0
	v_fmac_f32_e32 v14, v15, v14
	v_div_scale_f32 v15, vcc, 1.0, v12, 1.0
	v_mul_f32_e32 v16, v15, v14
	v_fma_f32 v17, -v13, v16, v15
	v_fmac_f32_e32 v16, v17, v14
	v_fma_f32 v13, -v13, v16, v15
	v_div_fmas_f32 v13, v13, v14, v16
	v_div_fixup_f32 v13, v13, v12, 1.0
	v_div_scale_f32 v12, s[0:1], v11, v11, 1.0
	v_rcp_f32_e32 v14, v12
	s_nop 0
	v_fma_f32 v15, -v12, v14, 1.0
	v_fmac_f32_e32 v14, v15, v14
	v_div_scale_f32 v15, vcc, 1.0, v11, 1.0
	v_mul_f32_e32 v16, v15, v14
	v_fma_f32 v17, -v12, v16, v15
	v_fmac_f32_e32 v16, v17, v14
	v_fma_f32 v12, -v12, v16, v15
	v_div_fmas_f32 v12, v12, v14, v16
	v_div_fixup_f32 v12, v12, v11, 1.0
	v_mov_b64_e32 v[14:15], s[34:35]
	flat_store_dwordx2 v[14:15], v[12:13]
	s_branch .LBB0_88
